# fc1 + stick-breaking blocks: 45 canonicalising v_max removed (min/max pairs read the MFMA result directly), bit-identical results
# speedup vs baseline: 1.0019x; 1.0019x over previous
.LBB0_353:
	v_mfma_f32_32x32x16_bf16 v[32:47], v[96:99], v[52:55], 0
	v_add_f32_e32 v139, 0, v130
	v_mov_b32_e32 v197, v131
	v_mfma_f32_32x32x16_bf16 v[32:47], v[100:103], v[56:59], v[32:47]
	v_mfma_f32_32x32x16_bf16 v[32:47], v[104:107], v[60:63], v[32:47]
	v_mfma_f32_32x32x16_bf16 v[32:47], v[108:111], v[68:71], v[32:47]
	s_nop 11
	v_exp_f32_e64 v130, -|v32|
	v_exp_f32_e64 v143, -|v33|
	v_exp_f32_e64 v145, -|v34|
	v_exp_f32_e64 v175, -|v35|
	v_exp_f32_e64 v176, -|v36|
	v_max_f32_e32 v181, 0, v33
	v_min_f32_e32 v182, 0, v33
	v_max_f32_e32 v183, 0, v35
	v_min_f32_e32 v184, 0, v35
	v_add_f32_e32 v33, 1.0, v130
	v_add_f32_e32 v35, 1.0, v143
	v_add_f32_e32 v130, 1.0, v145
	v_add_f32_e32 v143, 1.0, v175
	v_exp_f32_e64 v179, -|v37|
	v_log_f32_e32 v35, v35
	v_log_f32_e32 v178, v130
	v_log_f32_e32 v130, v143
	v_min_f32_e32 v147, 0, v34
	v_max_f32_e32 v34, 0, v34
	v_add_f32_e32 v145, 1.0, v176
	v_log_f32_e32 v176, v33
	v_log_f32_e32 v180, v145
	v_add_f32_e32 v33, v181, v35
	v_sub_f32_e32 v143, v182, v35
	v_sub_f32_e32 v145, v147, v178
	v_add_f32_e32 v35, v183, v130
	v_sub_f32_e32 v147, v184, v130
	v_add_f32_e32 v130, 1.0, v179
	v_log_f32_e32 v182, v130
	v_exp_f32_e64 v130, -|v38|
	v_max_f32_e32 v184, 0, v37
	v_min_f32_e32 v37, 0, v37
	v_min_f32_e32 v177, 0, v36
	v_max_f32_e32 v36, 0, v36
	v_sub_f32_e32 v198, v37, v182
	v_add_f32_e32 v37, 1.0, v130
	v_sub_f32_e32 v175, v177, v180
	v_log_f32_e32 v130, v37
	v_exp_f32_e64 v177, -|v39|
	v_min_f32_e32 v37, 0, v38
	v_max_f32_e32 v38, 0, v38
	v_sub_f32_e32 v199, v37, v130
	v_add_f32_e32 v37, 1.0, v177
	v_log_f32_e32 v37, v37
	v_exp_f32_e64 v179, -|v40|
	v_min_f32_e32 v177, 0, v39
	v_max_f32_e32 v39, 0, v39
	v_add_f32_e32 v39, v39, v37
	v_sub_f32_e32 v200, v177, v37
	v_add_f32_e32 v37, 1.0, v179
	v_log_f32_e32 v186, v37
	v_exp_f32_e64 v177, -|v41|
	v_min_f32_e32 v37, 0, v40
	v_max_f32_e32 v40, 0, v40
	v_sub_f32_e32 v201, v37, v186
	v_add_f32_e32 v37, 1.0, v177
	v_log_f32_e32 v37, v37
	v_exp_f32_e64 v179, -|v42|
	v_min_f32_e32 v177, 0, v41
	v_max_f32_e32 v41, 0, v41
	v_add_f32_e32 v41, v41, v37
	v_sub_f32_e32 v202, v177, v37
	v_add_f32_e32 v37, 1.0, v179
	v_log_f32_e32 v188, v37
	v_exp_f32_e64 v177, -|v43|
	v_min_f32_e32 v37, 0, v42
	v_max_f32_e32 v42, 0, v42
	v_sub_f32_e32 v203, v37, v188
	v_add_f32_e32 v37, 1.0, v177
	v_log_f32_e32 v37, v37
	v_exp_f32_e64 v179, -|v44|
	v_min_f32_e32 v177, 0, v43
	v_max_f32_e32 v43, 0, v43
	v_add_f32_e32 v43, v43, v37
	v_sub_f32_e32 v204, v177, v37
	v_add_f32_e32 v37, 1.0, v179
	v_log_f32_e32 v190, v37
	v_exp_f32_e64 v177, -|v45|
	v_min_f32_e32 v37, 0, v44
	v_max_f32_e32 v44, 0, v44
	v_sub_f32_e32 v205, v37, v190
	v_add_f32_e32 v37, 1.0, v177
	v_log_f32_e32 v192, v37
	v_max_f32_e32 v37, v45, v45
	v_exp_f32_e64 v45, -|v46|
	v_max_f32_e32 v194, 0, v37
	v_min_f32_e32 v37, 0, v37
	v_sub_f32_e32 v208, v37, v192
	v_add_f32_e32 v37, 1.0, v45
	v_log_f32_e32 v196, v37
	v_exp_f32_e64 v37, -|v47|
	v_min_f32_e32 v45, 0, v46
	v_max_f32_e32 v46, 0, v46
	v_add_f32_e32 v37, 1.0, v37
	v_log_f32_e32 v37, v37
	v_sub_f32_e32 v209, v45, v196
	v_max_f32_e32 v45, 0, v47
	v_min_f32_e32 v47, 0, v47
	v_sub_f32_e32 v210, v47, v37
	v_add_f32_e32 v47, v45, v37
	v_pk_add_f32 v[38:39], v[38:39], v[130:131]
	v_pk_add_f32 v[46:47], v[46:47], v[196:197]
	v_mov_b32_e32 v185, v38
	v_mov_b32_e32 v183, v39
	v_mov_b32_e32 v195, v46
	v_mov_b32_e32 v193, v47
	v_pk_add_f32 v[182:183], v[184:185], v[182:183]
	v_pk_add_f32 v[184:185], v[194:195], v[192:193]
	v_mov_b32_e32 v37, v182
	v_mov_b32_e32 v45, v184
	v_mov_b32_e32 v191, v185
	v_pk_add_f32 v[44:45], v[44:45], v[190:191]
	v_mov_b32_e32 v181, v183
	v_pk_add_f32 v[190:191], v[44:45], v[44:45] op_sel:[0,1] op_sel_hi:[1,0]
	v_pk_add_f32 v[36:37], v[36:37], v[180:181]
	v_mov_b32_e32 v189, v190
	v_pk_add_f32 v[180:181], v[36:37], v[36:37] op_sel:[0,1] op_sel_hi:[1,0]
	v_pk_add_f32 v[42:43], v[42:43], v[188:189]
	v_mov_b32_e32 v179, v180
	v_pk_add_f32 v[188:189], v[42:43], v[42:43] op_sel:[0,1] op_sel_hi:[1,0]
	v_pk_add_f32 v[34:35], v[34:35], v[178:179]
	v_mov_b32_e32 v187, v188
	v_pk_add_f32 v[178:179], v[34:35], v[34:35] op_sel:[0,1] op_sel_hi:[1,0]
	v_pk_add_f32 v[40:41], v[40:41], v[186:187]
	v_min_f32_e32 v141, 0, v32
	v_max_f32_e32 v32, 0, v32
	v_pk_add_f32 v[186:187], v[40:41], v[40:41] op_sel:[0,1] op_sel_hi:[1,0]
	v_mov_b32_e32 v177, v178
	ds_bpermute_b32 v40, v129, v186
	v_pk_add_f32 v[32:33], v[32:33], v[176:177]
	v_sub_f32_e32 v141, v141, v176
	v_pk_add_f32 v[176:177], v[32:33], v[32:33] op_sel:[0,1] op_sel_hi:[1,0]
	ds_bpermute_b32 v42, v129, v176
	s_waitcnt lgkmcnt(1)
	v_cndmask_b32_e64 v32, 0, v40, s[0:1]
	v_add_f32_e32 v36, v139, v32
	v_add_f32_e32 v32, v139, v186
	v_add_f32_e32 v32, v32, v40
	s_waitcnt lgkmcnt(0)
	v_cndmask_b32_e64 v34, 0, v42, s[0:1]
	v_add_f32_e32 v32, v34, v32
	v_sub_f32_e32 v34, v141, v32
	v_sub_f32_e32 v38, v145, v32
	v_sub_f32_e32 v44, v175, v32
	v_sub_f32_e32 v33, v34, v33
	v_sub_f32_e32 v34, v143, v32
	v_sub_f32_e32 v35, v38, v35
	v_sub_f32_e32 v38, v147, v32
	v_sub_f32_e32 v37, v44, v37
	v_sub_f32_e32 v44, v198, v32
	v_sub_f32_e32 v46, v199, v32
	v_sub_f32_e32 v32, v200, v32
	v_sub_f32_e32 v39, v46, v39
	v_exp_f32_e32 v46, v32
	v_sub_f32_e32 v32, v201, v36
	v_sub_f32_e32 v32, v32, v41
	v_exp_f32_e32 v41, v32
	v_sub_f32_e32 v32, v202, v36
	v_sub_f32_e32 v32, v32, v188
	v_exp_f32_e32 v130, v32
	v_sub_f32_e32 v32, v203, v36
	v_sub_f32_e32 v32, v32, v43
	v_exp_f32_e32 v43, v32
	v_sub_f32_e32 v32, v204, v36
	v_sub_f32_e32 v32, v32, v190
	v_sub_f32_e32 v34, v34, v178
	v_sub_f32_e32 v38, v38, v180
	v_sub_f32_e32 v44, v44, v183
	v_exp_f32_e32 v141, v32
	v_sub_f32_e32 v32, v205, v36
	v_exp_f32_e32 v33, v33
	v_exp_f32_e32 v34, v34
	v_exp_f32_e32 v35, v35
	v_exp_f32_e32 v38, v38
	v_exp_f32_e32 v37, v37
	v_exp_f32_e32 v44, v44
	v_exp_f32_e32 v39, v39
	v_sub_f32_e32 v32, v32, v45
	v_exp_f32_e32 v45, v32
	v_sub_f32_e32 v32, v208, v36
	v_sub_f32_e32 v32, v32, v185
	v_exp_f32_e32 v143, v32
	v_sub_f32_e32 v32, v209, v36
	v_sub_f32_e32 v47, v32, v47
	v_cvt_pk_bf16_f32 v32, v33, v34
	v_cvt_pk_bf16_f32 v33, v35, v38
	v_cvt_pk_bf16_f32 v34, v37, v44
	v_cvt_pk_bf16_f32 v35, v39, v46
	v_sub_f32_e32 v36, v210, v36
	v_exp_f32_e32 v39, v47
	v_exp_f32_e32 v44, v36
	v_mfma_f32_32x32x16_bf16 v[0:15], v[32:35], v[112:115], v[0:15]
	v_cvt_pk_bf16_f32 v36, v41, v130
	v_cvt_pk_bf16_f32 v37, v43, v141
	v_cvt_pk_bf16_f32 v38, v45, v143
	v_cvt_pk_bf16_f32 v39, v39, v44
	v_mov_b32_e32 v43, v176
	v_mov_b32_e32 v41, v186
	v_mfma_f32_32x32x16_bf16 v[16:31], v[32:35], v[120:123], v[16:31]
	v_add_f32_e64 v32, v42, v40
	v_add_f32_e64 v33, v43, v41
	v_add_f32_e32 v32, v32, v33
	v_add_f32_e32 v139, v139, v32
	v_cmp_lt_f32_e32 vcc, s76, v139
	s_cmp_eq_u64 vcc, exec
	s_cselect_b64 s[94:95], -1, 0
	v_mfma_f32_32x32x16_bf16 v[0:15], v[36:39], v[116:119], v[0:15]
	s_cmp_lt_u32 s89, 2
	s_cselect_b64 s[96:97], -1, 0
	s_or_b64 s[94:95], s[94:95], s[96:97]
	s_and_b64 vcc, exec, s[94:95]
	v_mfma_f32_32x32x16_bf16 v[16:31], v[36:39], v[124:127], v[16:31]
	s_cbranch_vccnz .LBB0_347
	s_cmp_lt_u32 s89, 3
	s_mov_b64 s[94:95], -1
	s_cbranch_scc1 .LBB0_356
	s_add_i32 s91, s89, -3
	s_mov_b64 s[94:95], 0
	s_branch .LBB0_358

.LBB0_362:
	s_waitcnt vmcnt(7)
	v_mfma_f32_32x32x16_bf16 v[32:47], v[48:51], v[52:55], 0
	v_mov_b32_e32 v197, v131
	s_mov_b32 s3, s89
	s_waitcnt vmcnt(6)
	v_mfma_f32_32x32x16_bf16 v[32:47], v[64:67], v[56:59], v[32:47]
	s_waitcnt vmcnt(5)
	v_mfma_f32_32x32x16_bf16 v[32:47], v[72:75], v[60:63], v[32:47]
	s_waitcnt vmcnt(4)
	v_mfma_f32_32x32x16_bf16 v[32:47], v[76:79], v[68:71], v[32:47]
	s_nop 11
	v_exp_f32_e64 v130, -|v32|
	v_exp_f32_e64 v143, -|v33|
	v_exp_f32_e64 v145, -|v34|
	v_exp_f32_e64 v175, -|v35|
	v_exp_f32_e64 v176, -|v36|
	v_max_f32_e32 v181, 0, v33
	v_min_f32_e32 v182, 0, v33
	v_max_f32_e32 v183, 0, v35
	v_min_f32_e32 v184, 0, v35
	v_add_f32_e32 v33, 1.0, v130
	v_add_f32_e32 v35, 1.0, v143
	v_add_f32_e32 v130, 1.0, v145
	v_add_f32_e32 v143, 1.0, v175
	v_exp_f32_e64 v179, -|v37|
	v_log_f32_e32 v35, v35
	v_log_f32_e32 v178, v130
	v_log_f32_e32 v130, v143
	v_min_f32_e32 v147, 0, v34
	v_max_f32_e32 v34, 0, v34
	v_add_f32_e32 v145, 1.0, v176
	v_log_f32_e32 v176, v33
	v_log_f32_e32 v180, v145
	v_add_f32_e32 v33, v181, v35
	v_sub_f32_e32 v143, v182, v35
	v_sub_f32_e32 v145, v147, v178
	v_add_f32_e32 v35, v183, v130
	v_sub_f32_e32 v147, v184, v130
	v_add_f32_e32 v130, 1.0, v179
	v_log_f32_e32 v182, v130
	v_exp_f32_e64 v130, -|v38|
	v_max_f32_e32 v184, 0, v37
	v_min_f32_e32 v37, 0, v37
	v_min_f32_e32 v177, 0, v36
	v_max_f32_e32 v36, 0, v36
	v_sub_f32_e32 v198, v37, v182
	v_add_f32_e32 v37, 1.0, v130
	v_sub_f32_e32 v175, v177, v180
	v_log_f32_e32 v130, v37
	v_exp_f32_e64 v177, -|v39|
	v_min_f32_e32 v37, 0, v38
	v_max_f32_e32 v38, 0, v38
	v_sub_f32_e32 v199, v37, v130
	v_add_f32_e32 v37, 1.0, v177
	v_log_f32_e32 v37, v37
	v_exp_f32_e64 v179, -|v40|
	v_min_f32_e32 v177, 0, v39
	v_max_f32_e32 v39, 0, v39
	v_add_f32_e32 v39, v39, v37
	v_sub_f32_e32 v200, v177, v37
	v_add_f32_e32 v37, 1.0, v179
	v_log_f32_e32 v186, v37
	v_exp_f32_e64 v177, -|v41|
	v_min_f32_e32 v37, 0, v40
	v_max_f32_e32 v40, 0, v40
	v_sub_f32_e32 v201, v37, v186
	v_add_f32_e32 v37, 1.0, v177
	v_log_f32_e32 v37, v37
	v_exp_f32_e64 v179, -|v42|
	v_min_f32_e32 v177, 0, v41
	v_max_f32_e32 v41, 0, v41
	v_add_f32_e32 v41, v41, v37
	v_sub_f32_e32 v202, v177, v37
	v_add_f32_e32 v37, 1.0, v179
	v_log_f32_e32 v188, v37
	v_exp_f32_e64 v177, -|v43|
	v_min_f32_e32 v37, 0, v42
	v_max_f32_e32 v42, 0, v42
	v_sub_f32_e32 v203, v37, v188
	v_add_f32_e32 v37, 1.0, v177
	v_log_f32_e32 v37, v37
	v_exp_f32_e64 v179, -|v44|
	v_min_f32_e32 v177, 0, v43
	v_max_f32_e32 v43, 0, v43
	v_add_f32_e32 v43, v43, v37
	v_sub_f32_e32 v204, v177, v37
	v_add_f32_e32 v37, 1.0, v179
	v_log_f32_e32 v190, v37
	v_exp_f32_e64 v177, -|v45|
	v_min_f32_e32 v37, 0, v44
	v_max_f32_e32 v44, 0, v44
	v_sub_f32_e32 v205, v37, v190
	v_add_f32_e32 v37, 1.0, v177
	v_log_f32_e32 v192, v37
	v_max_f32_e32 v37, v45, v45
	v_exp_f32_e64 v45, -|v46|
	v_max_f32_e32 v194, 0, v37
	v_min_f32_e32 v37, 0, v37
	v_sub_f32_e32 v208, v37, v192
	v_add_f32_e32 v37, 1.0, v45
	v_log_f32_e32 v196, v37
	v_exp_f32_e64 v37, -|v47|
	v_min_f32_e32 v45, 0, v46
	v_max_f32_e32 v46, 0, v46
	v_add_f32_e32 v37, 1.0, v37
	v_log_f32_e32 v37, v37
	v_sub_f32_e32 v209, v45, v196
	v_max_f32_e32 v45, 0, v47
	v_min_f32_e32 v47, 0, v47
	v_sub_f32_e32 v210, v47, v37
	v_add_f32_e32 v47, v45, v37
	v_pk_add_f32 v[38:39], v[38:39], v[130:131]
	v_pk_add_f32 v[46:47], v[46:47], v[196:197]
	v_mov_b32_e32 v185, v38
	v_mov_b32_e32 v183, v39
	v_mov_b32_e32 v195, v46
	v_mov_b32_e32 v193, v47
	v_pk_add_f32 v[182:183], v[184:185], v[182:183]
	v_pk_add_f32 v[184:185], v[194:195], v[192:193]
	v_mov_b32_e32 v37, v182
	v_mov_b32_e32 v45, v184
	v_mov_b32_e32 v191, v185
	v_pk_add_f32 v[44:45], v[44:45], v[190:191]
	v_mov_b32_e32 v181, v183
	v_pk_add_f32 v[190:191], v[44:45], v[44:45] op_sel:[0,1] op_sel_hi:[1,0]
	v_pk_add_f32 v[36:37], v[36:37], v[180:181]
	v_mov_b32_e32 v189, v190
	v_pk_add_f32 v[180:181], v[36:37], v[36:37] op_sel:[0,1] op_sel_hi:[1,0]
	v_pk_add_f32 v[42:43], v[42:43], v[188:189]
	v_mov_b32_e32 v179, v180
	v_pk_add_f32 v[188:189], v[42:43], v[42:43] op_sel:[0,1] op_sel_hi:[1,0]
	v_pk_add_f32 v[34:35], v[34:35], v[178:179]
	v_mov_b32_e32 v187, v188
	v_pk_add_f32 v[178:179], v[34:35], v[34:35] op_sel:[0,1] op_sel_hi:[1,0]
	v_pk_add_f32 v[40:41], v[40:41], v[186:187]
	v_min_f32_e32 v141, 0, v32
	v_max_f32_e32 v32, 0, v32
	v_pk_add_f32 v[186:187], v[40:41], v[40:41] op_sel:[0,1] op_sel_hi:[1,0]
	v_mov_b32_e32 v177, v178
	ds_bpermute_b32 v40, v129, v186
	v_pk_add_f32 v[32:33], v[32:33], v[176:177]
	v_sub_f32_e32 v141, v141, v176
	v_pk_add_f32 v[176:177], v[32:33], v[32:33] op_sel:[0,1] op_sel_hi:[1,0]
	ds_bpermute_b32 v42, v129, v176
	s_waitcnt lgkmcnt(1)
	v_cndmask_b32_e64 v32, 0, v40, s[0:1]
	v_add_f32_e32 v36, v139, v32
	v_add_f32_e32 v32, v139, v186
	v_add_f32_e32 v32, v32, v40
	s_waitcnt lgkmcnt(0)
	v_cndmask_b32_e64 v34, 0, v42, s[0:1]
	v_add_f32_e32 v32, v34, v32
	v_sub_f32_e32 v34, v141, v32
	v_sub_f32_e32 v38, v145, v32
	v_sub_f32_e32 v44, v175, v32
	v_sub_f32_e32 v33, v34, v33
	v_sub_f32_e32 v34, v143, v32
	v_sub_f32_e32 v35, v38, v35
	v_sub_f32_e32 v38, v147, v32
	v_sub_f32_e32 v37, v44, v37
	v_sub_f32_e32 v44, v198, v32
	v_sub_f32_e32 v46, v199, v32
	v_sub_f32_e32 v32, v200, v32
	v_sub_f32_e32 v39, v46, v39
	v_exp_f32_e32 v46, v32
	v_sub_f32_e32 v32, v201, v36
	v_sub_f32_e32 v32, v32, v41
	v_exp_f32_e32 v41, v32
	v_sub_f32_e32 v32, v202, v36
	v_sub_f32_e32 v32, v32, v188
	v_exp_f32_e32 v130, v32
	v_sub_f32_e32 v32, v203, v36
	v_sub_f32_e32 v32, v32, v43
	v_exp_f32_e32 v43, v32
	v_sub_f32_e32 v32, v204, v36
	v_sub_f32_e32 v32, v32, v190
	v_sub_f32_e32 v34, v34, v178
	v_sub_f32_e32 v38, v38, v180
	v_sub_f32_e32 v44, v44, v183
	v_exp_f32_e32 v141, v32
	v_sub_f32_e32 v32, v205, v36
	v_exp_f32_e32 v33, v33
	v_exp_f32_e32 v34, v34
	v_exp_f32_e32 v35, v35
	v_exp_f32_e32 v38, v38
	v_exp_f32_e32 v37, v37
	v_exp_f32_e32 v44, v44
	v_exp_f32_e32 v39, v39
	v_sub_f32_e32 v32, v32, v45
	v_exp_f32_e32 v45, v32
	v_sub_f32_e32 v32, v208, v36
	v_sub_f32_e32 v32, v32, v185
	v_exp_f32_e32 v143, v32
	v_sub_f32_e32 v32, v209, v36
	v_sub_f32_e32 v47, v32, v47
	v_cvt_pk_bf16_f32 v32, v33, v34
	v_cvt_pk_bf16_f32 v33, v35, v38
	v_cvt_pk_bf16_f32 v34, v37, v44
	v_cvt_pk_bf16_f32 v35, v39, v46
	v_sub_f32_e32 v36, v210, v36
	v_exp_f32_e32 v39, v47
	v_exp_f32_e32 v44, v36
	s_waitcnt vmcnt(3)
	v_mfma_f32_32x32x16_bf16 v[0:15], v[32:35], v[80:83], v[0:15]
	v_cvt_pk_bf16_f32 v36, v41, v130
	v_cvt_pk_bf16_f32 v37, v43, v141
	v_cvt_pk_bf16_f32 v38, v45, v143
	v_cvt_pk_bf16_f32 v39, v39, v44
	v_mov_b32_e32 v43, v176
	v_mov_b32_e32 v41, v186
	s_waitcnt vmcnt(1)
	v_mfma_f32_32x32x16_bf16 v[16:31], v[32:35], v[88:91], v[16:31]
	v_add_f32_e64 v32, v42, v40
	v_add_f32_e64 v33, v43, v41
	v_add_f32_e32 v32, v32, v33
	v_add_f32_e32 v139, v139, v32
	v_cmp_lt_f32_e32 vcc, s76, v139
	s_cmp_eq_u64 vcc, exec
	s_cselect_b64 s[94:95], -1, 0
	v_mfma_f32_32x32x16_bf16 v[0:15], v[36:39], v[84:87], v[0:15]
	s_cmp_lt_i32 s89, 3
	s_cselect_b64 s[96:97], -1, 0
	s_or_b64 s[96:97], s[94:95], s[96:97]
	s_mov_b64 s[94:95], -1
	s_and_b64 vcc, exec, s[96:97]
	s_waitcnt vmcnt(0)
	v_mfma_f32_32x32x16_bf16 v[16:31], v[36:39], v[92:95], v[16:31]
	s_cbranch_vccnz .LBB0_360
	s_add_i32 s89, s3, -2
	s_cmp_lt_u32 s89, 2
	s_cbranch_scc1 .LBB0_365
	s_add_i32 s91, s3, -4
	v_mad_u64_u32 v[32:33], s[94:95], s91, v173, v[148:149]
	global_load_dwordx4 v[48:51], v[32:33], off offset:1024
	global_load_dwordx4 v[64:67], v[32:33], off offset:1056
	global_load_dwordx4 v[72:75], v[32:33], off offset:1088
	global_load_dwordx4 v[76:79], v[32:33], off offset:1120
	v_lshl_add_u64 v[32:33], s[50:51], 1, v[150:151]
	global_load_dwordx4 v[80:83], v[32:33], off
	global_load_dwordx4 v[84:87], v[32:33], off offset:32
	v_add_co_u32_e32 v32, vcc, 0x100000, v32
	s_nop 1
	v_addc_co_u32_e32 v33, vcc, 0, v33, vcc
	global_load_dwordx4 v[88:91], v[32:33], off
	global_load_dwordx4 v[92:95], v[32:33], off offset:32
.LBB0_365:
	v_mfma_f32_32x32x16_bf16 v[32:47], v[96:99], v[52:55], 0
	v_mov_b32_e32 v197, v131
	v_mfma_f32_32x32x16_bf16 v[32:47], v[100:103], v[56:59], v[32:47]
	v_mfma_f32_32x32x16_bf16 v[32:47], v[104:107], v[60:63], v[32:47]
	v_mfma_f32_32x32x16_bf16 v[32:47], v[108:111], v[68:71], v[32:47]
	s_nop 11
	v_exp_f32_e64 v130, -|v32|
	v_exp_f32_e64 v143, -|v33|
	v_exp_f32_e64 v145, -|v34|
	v_exp_f32_e64 v175, -|v35|
	v_exp_f32_e64 v176, -|v36|
	v_max_f32_e32 v181, 0, v33
	v_min_f32_e32 v182, 0, v33
	v_max_f32_e32 v183, 0, v35
	v_min_f32_e32 v184, 0, v35
	v_add_f32_e32 v33, 1.0, v130
	v_add_f32_e32 v35, 1.0, v143
	v_add_f32_e32 v130, 1.0, v145
	v_add_f32_e32 v143, 1.0, v175
	v_exp_f32_e64 v179, -|v37|
	v_log_f32_e32 v35, v35
	v_log_f32_e32 v178, v130
	v_log_f32_e32 v130, v143
	v_min_f32_e32 v147, 0, v34
	v_max_f32_e32 v34, 0, v34
	v_add_f32_e32 v145, 1.0, v176
	v_log_f32_e32 v176, v33
	v_log_f32_e32 v180, v145
	v_add_f32_e32 v33, v181, v35
	v_sub_f32_e32 v143, v182, v35
	v_sub_f32_e32 v145, v147, v178
	v_add_f32_e32 v35, v183, v130
	v_sub_f32_e32 v147, v184, v130
	v_add_f32_e32 v130, 1.0, v179
	v_log_f32_e32 v182, v130
	v_exp_f32_e64 v130, -|v38|
	v_max_f32_e32 v184, 0, v37
	v_min_f32_e32 v37, 0, v37
	v_min_f32_e32 v177, 0, v36
	v_max_f32_e32 v36, 0, v36
	v_sub_f32_e32 v198, v37, v182
	v_add_f32_e32 v37, 1.0, v130
	v_sub_f32_e32 v175, v177, v180
	v_log_f32_e32 v130, v37
	v_exp_f32_e64 v177, -|v39|
	v_min_f32_e32 v37, 0, v38
	v_max_f32_e32 v38, 0, v38
	v_sub_f32_e32 v199, v37, v130
	v_add_f32_e32 v37, 1.0, v177
	v_log_f32_e32 v37, v37
	v_exp_f32_e64 v179, -|v40|
	v_min_f32_e32 v177, 0, v39
	v_max_f32_e32 v39, 0, v39
	v_add_f32_e32 v39, v39, v37
	v_sub_f32_e32 v200, v177, v37
	v_add_f32_e32 v37, 1.0, v179
	v_log_f32_e32 v186, v37
	v_exp_f32_e64 v177, -|v41|
	v_min_f32_e32 v37, 0, v40
	v_max_f32_e32 v40, 0, v40
	v_sub_f32_e32 v201, v37, v186
	v_add_f32_e32 v37, 1.0, v177
	v_log_f32_e32 v37, v37
	v_exp_f32_e64 v179, -|v42|
	v_min_f32_e32 v177, 0, v41
	v_max_f32_e32 v41, 0, v41
	v_add_f32_e32 v41, v41, v37
	v_sub_f32_e32 v202, v177, v37
	v_add_f32_e32 v37, 1.0, v179
	v_log_f32_e32 v188, v37
	v_exp_f32_e64 v177, -|v43|
	v_min_f32_e32 v37, 0, v42
	v_max_f32_e32 v42, 0, v42
	v_sub_f32_e32 v203, v37, v188
	v_add_f32_e32 v37, 1.0, v177
	v_log_f32_e32 v37, v37
	v_exp_f32_e64 v179, -|v44|
	v_min_f32_e32 v177, 0, v43
	v_max_f32_e32 v43, 0, v43
	v_add_f32_e32 v43, v43, v37
	v_sub_f32_e32 v204, v177, v37
	v_add_f32_e32 v37, 1.0, v179
	v_log_f32_e32 v190, v37
	v_exp_f32_e64 v177, -|v45|
	v_min_f32_e32 v37, 0, v44
	v_max_f32_e32 v44, 0, v44
	v_sub_f32_e32 v205, v37, v190
	v_add_f32_e32 v37, 1.0, v177
	v_log_f32_e32 v192, v37
	v_max_f32_e32 v37, v45, v45
	v_exp_f32_e64 v45, -|v46|
	v_max_f32_e32 v194, 0, v37
	v_min_f32_e32 v37, 0, v37
	v_sub_f32_e32 v208, v37, v192
	v_add_f32_e32 v37, 1.0, v45
	v_log_f32_e32 v196, v37
	v_exp_f32_e64 v37, -|v47|
	v_min_f32_e32 v45, 0, v46
	v_max_f32_e32 v46, 0, v46
	v_add_f32_e32 v37, 1.0, v37
	v_log_f32_e32 v37, v37
	v_sub_f32_e32 v209, v45, v196
	v_max_f32_e32 v45, 0, v47
	v_min_f32_e32 v47, 0, v47
	v_sub_f32_e32 v210, v47, v37
	v_add_f32_e32 v47, v45, v37
	v_pk_add_f32 v[38:39], v[38:39], v[130:131]
	v_pk_add_f32 v[46:47], v[46:47], v[196:197]
	v_mov_b32_e32 v185, v38
	v_mov_b32_e32 v183, v39
	v_mov_b32_e32 v195, v46
	v_mov_b32_e32 v193, v47
	v_pk_add_f32 v[182:183], v[184:185], v[182:183]
	v_pk_add_f32 v[184:185], v[194:195], v[192:193]
	v_mov_b32_e32 v37, v182
	v_mov_b32_e32 v45, v184
	v_mov_b32_e32 v191, v185
	v_pk_add_f32 v[44:45], v[44:45], v[190:191]
	v_mov_b32_e32 v181, v183
	v_pk_add_f32 v[190:191], v[44:45], v[44:45] op_sel:[0,1] op_sel_hi:[1,0]
	v_pk_add_f32 v[36:37], v[36:37], v[180:181]
	v_mov_b32_e32 v189, v190
	v_pk_add_f32 v[180:181], v[36:37], v[36:37] op_sel:[0,1] op_sel_hi:[1,0]
	v_pk_add_f32 v[42:43], v[42:43], v[188:189]
	v_mov_b32_e32 v179, v180
	v_pk_add_f32 v[188:189], v[42:43], v[42:43] op_sel:[0,1] op_sel_hi:[1,0]
	v_pk_add_f32 v[34:35], v[34:35], v[178:179]
	v_mov_b32_e32 v187, v188
	v_pk_add_f32 v[178:179], v[34:35], v[34:35] op_sel:[0,1] op_sel_hi:[1,0]
	v_pk_add_f32 v[40:41], v[40:41], v[186:187]
	v_min_f32_e32 v141, 0, v32
	v_max_f32_e32 v32, 0, v32
	v_pk_add_f32 v[186:187], v[40:41], v[40:41] op_sel:[0,1] op_sel_hi:[1,0]
	v_mov_b32_e32 v177, v178
	ds_bpermute_b32 v40, v129, v186
	v_pk_add_f32 v[32:33], v[32:33], v[176:177]
	v_sub_f32_e32 v141, v141, v176
	v_pk_add_f32 v[176:177], v[32:33], v[32:33] op_sel:[0,1] op_sel_hi:[1,0]
	ds_bpermute_b32 v42, v129, v176
	s_waitcnt lgkmcnt(1)
	v_cndmask_b32_e64 v32, 0, v40, s[0:1]
	v_add_f32_e32 v36, v139, v32
	v_add_f32_e32 v32, v139, v186
	v_add_f32_e32 v32, v32, v40
	s_waitcnt lgkmcnt(0)
	v_cndmask_b32_e64 v34, 0, v42, s[0:1]
	v_add_f32_e32 v32, v34, v32
	v_sub_f32_e32 v34, v141, v32
	v_sub_f32_e32 v38, v145, v32
	v_sub_f32_e32 v44, v175, v32
	v_sub_f32_e32 v33, v34, v33
	v_sub_f32_e32 v34, v143, v32
	v_sub_f32_e32 v35, v38, v35
	v_sub_f32_e32 v38, v147, v32
	v_sub_f32_e32 v37, v44, v37
	v_sub_f32_e32 v44, v198, v32
	v_sub_f32_e32 v46, v199, v32
	v_sub_f32_e32 v32, v200, v32
	v_sub_f32_e32 v39, v46, v39
	v_exp_f32_e32 v46, v32
	v_sub_f32_e32 v32, v201, v36
	v_sub_f32_e32 v32, v32, v41
	v_exp_f32_e32 v41, v32
	v_sub_f32_e32 v32, v202, v36
	v_sub_f32_e32 v32, v32, v188
	v_exp_f32_e32 v130, v32
	v_sub_f32_e32 v32, v203, v36
	v_sub_f32_e32 v32, v32, v43
	v_exp_f32_e32 v43, v32
	v_sub_f32_e32 v32, v204, v36
	v_sub_f32_e32 v32, v32, v190
	v_sub_f32_e32 v34, v34, v178
	v_sub_f32_e32 v38, v38, v180
	v_sub_f32_e32 v44, v44, v183
	v_exp_f32_e32 v141, v32
	v_sub_f32_e32 v32, v205, v36
	v_exp_f32_e32 v33, v33
	v_exp_f32_e32 v34, v34
	v_exp_f32_e32 v35, v35
	v_exp_f32_e32 v38, v38
	v_exp_f32_e32 v37, v37
	v_exp_f32_e32 v44, v44
	v_exp_f32_e32 v39, v39
	v_sub_f32_e32 v32, v32, v45
	v_exp_f32_e32 v45, v32
	v_sub_f32_e32 v32, v208, v36
	v_sub_f32_e32 v32, v32, v185
	v_exp_f32_e32 v143, v32
	v_sub_f32_e32 v32, v209, v36
	v_sub_f32_e32 v47, v32, v47
	v_cvt_pk_bf16_f32 v32, v33, v34
	v_cvt_pk_bf16_f32 v33, v35, v38
	v_cvt_pk_bf16_f32 v34, v37, v44
	v_cvt_pk_bf16_f32 v35, v39, v46
	v_sub_f32_e32 v36, v210, v36
	v_exp_f32_e32 v39, v47
	v_exp_f32_e32 v44, v36
	v_mfma_f32_32x32x16_bf16 v[0:15], v[32:35], v[112:115], v[0:15]
	v_cvt_pk_bf16_f32 v36, v41, v130
	v_cvt_pk_bf16_f32 v37, v43, v141
	v_cvt_pk_bf16_f32 v38, v45, v143
	v_cvt_pk_bf16_f32 v39, v39, v44
	v_mov_b32_e32 v43, v176
	v_mov_b32_e32 v41, v186
	v_mfma_f32_32x32x16_bf16 v[16:31], v[32:35], v[120:123], v[16:31]
	v_add_f32_e64 v32, v42, v40
	v_add_f32_e64 v33, v43, v41
	v_add_f32_e32 v32, v32, v33
	v_add_f32_e32 v139, v139, v32
	v_cmp_lt_f32_e32 vcc, s76, v139
	s_cmp_eq_u64 vcc, exec
	s_cselect_b64 s[94:95], -1, 0
	v_mfma_f32_32x32x16_bf16 v[0:15], v[36:39], v[116:119], v[0:15]
	s_cmp_lt_u32 s3, 4
	s_cselect_b64 s[96:97], -1, 0
	s_or_b64 s[96:97], s[94:95], s[96:97]
	s_mov_b64 s[94:95], -1
	s_and_b64 vcc, exec, s[96:97]
	s_mov_b64 s[96:97], -1
	v_mfma_f32_32x32x16_bf16 v[16:31], v[36:39], v[124:127], v[16:31]
	s_cbranch_vccnz .LBB0_361
	s_sub_i32 s50, s50, 64
	s_cmp_gt_u32 s89, 2
	s_mov_b64 s[94:95], 0
	s_cselect_b64 s[96:97], -1, 0
	s_branch .LBB0_361

.LBB0_371:
	s_nop 0
	s_nop 0
	s_nop 0
	s_nop 0
	s_nop 0
	s_nop 0
	s_nop 0
	s_nop 0
	s_nop 0
	s_nop 0
	s_nop 0
	s_nop 0
	s_nop 0
	s_waitcnt vmcnt(0)
	s_waitcnt vmcnt(10)
	v_mov_b32_e32 v102, v206
	s_barrier
	v_readlane_b32 s78, v238, 5
	v_readfirstlane_b32 s3, v102
	s_cmp_gt_u32 s3, 63
	s_mov_b64 s[0:1], -1
	v_readlane_b32 s79, v238, 6
	v_readlane_b32 s77, v238, 7
	s_cbranch_scc0 .LBB0_449
	s_mov_b32 s0, s77
	s_mov_b32 s26, s78
	s_and_b32 s1, s26, 7
	s_cmp_lg_u32 s1, 0
	s_cbranch_scc1 .LBB0_374
	s_ashr_i32 s4, s0, 31
	s_lshr_b32 s4, s4, 29
	s_add_i32 s4, s0, s4
	s_ashr_i32 s5, s4, 3
	s_and_b32 s4, s4, -8
	s_ashr_i32 s1, s26, 3
	s_sub_i32 s0, s0, s4
	s_mul_i32 s0, s0, s1
	s_add_i32 s0, s0, s5
